# P2 start staggered 20us for odd-XCD workgroups to interleave epilogue store bursts with the other half's K-loops
# baseline (speedup 1.0000x reference)
.LBB0_124:
	s_andn2_b64 vcc, exec, s[0:1]
	s_cbranch_vccnz .LBB0_170
	s_bitcmp1_b32 s92, 0
	s_cbranch_scc0 .Lstg_skip_p2
	s_memrealtime s[98:99]
	s_waitcnt lgkmcnt(0)
.Lstg_spin_p2:
	s_sleep 8
	s_memrealtime s[100:101]
	s_waitcnt lgkmcnt(0)
	s_sub_u32 s100, s100, s98
	s_cmp_lt_u32 s100, 2000
	s_cbranch_scc1 .Lstg_spin_p2
.Lstg_skip_p2:
	v_bfe_i32 v4, v2, 27, 1
	v_lshlrev_b32_e32 v6, 4, v2
	v_lshrrev_b32_e32 v4, 22, v4
	v_ashrrev_i32_e32 v3, 31, v2
	v_add_u32_e32 v4, v6, v4
	v_lshrrev_b32_e32 v3, 26, v3
	v_and_b32_e32 v4, 0xfffffc00, v4
	v_add_u32_e32 v3, v2, v3
	v_sub_u32_e32 v4, v6, v4
	v_ashrrev_i32_e32 v3, 6, v3
	v_lshrrev_b32_e32 v5, 4, v4
	v_bitop3_b32 v5, v5, v4, 32 bitop3:0x6c
	v_lshlrev_b32_e32 v4, 3, v3
	v_and_b32_e32 v7, -16, v4
	v_ashrrev_i32_e32 v4, 31, v5
	v_lshrrev_b32_e32 v4, 26, v4
	v_add_u32_e32 v8, v5, v4
	v_ashrrev_i32_e32 v4, 6, v8
	v_and_b32_e32 v8, 0xc0, v8
	v_sub_u32_e32 v5, v5, v8
	v_lshlrev_b32_e32 v9, 5, v3
	v_ashrrev_i16_sdwa v5, v231, sext(v5) dst_sel:DWORD dst_unused:UNUSED_PAD src0_sel:DWORD src1_sel:BYTE_0
	v_and_b32_e32 v9, 32, v9
	v_bfe_i32 v5, v5, 0, 16
	v_add_u32_e32 v7, v4, v7
	v_and_b32_e32 v11, 3, v4
	s_mov_b32 s1, 0xfffe0
	v_add_lshl_u32 v9, v9, v5, 1
	v_lshlrev_b32_e32 v8, 1, v7
	v_lshrrev_b32_e32 v10, 2, v7
	v_and_or_b32 v11, v7, s1, v11
	v_lshl_add_u32 v130, v7, 12, v9
	v_add_u32_e32 v7, 0x2000, v6
	v_ashrrev_i32_e32 v6, 31, v7
	v_lshrrev_b32_e32 v6, 22, v6
	v_and_b32_e32 v8, 24, v8
	v_and_b32_e32 v10, 4, v10
	v_add_u32_e32 v6, v7, v6
	v_or3_b32 v8, v11, v10, v8
	v_ashrrev_i32_e32 v6, 10, v6
	v_lshl_add_u32 v194, v8, 12, v9
	v_mul_i32_i24_e32 v8, 0x400, v6
	v_sub_u32_e32 v7, v7, v8
	v_lshrrev_b32_e32 v8, 4, v7
	v_bitop3_b32 v8, v8, v7, 32 bitop3:0x6c
	v_lshlrev_b32_e32 v7, 3, v6
	v_and_b32_e32 v9, -16, v7
	v_ashrrev_i32_e32 v7, 31, v8
	v_lshrrev_b32_e32 v7, 26, v7
	v_add_u32_e32 v10, v8, v7
	v_ashrrev_i32_e32 v7, 6, v10
	v_add_u32_e32 v9, v7, v9
	v_and_b32_e32 v10, 0xc0, v10
	v_and_b32_e32 v13, 3, v7
	v_sub_u32_e32 v8, v8, v10
	v_and_or_b32 v13, v9, s1, v13
	s_ashr_i32 s1, s12, 6
	v_lshlrev_b32_e32 v11, 5, v6
	v_ashrrev_i16_sdwa v8, v231, sext(v8) dst_sel:DWORD dst_unused:UNUSED_PAD src0_sel:DWORD src1_sel:BYTE_0
	v_lshlrev_b32_e32 v10, 1, v9
	v_lshrrev_b32_e32 v12, 2, v9
	s_lshl_b32 s55, s1, 10
	v_and_b32_e32 v11, 32, v11
	v_bfe_i32 v8, v8, 0, 16
	v_and_b32_e32 v10, 24, v10
	v_and_b32_e32 v12, 4, v12
	s_add_i32 s83, s55, 0x10000
	v_or3_b32 v10, v13, v12, v10
	v_add_lshl_u32 v11, v11, v8, 1
	s_mov_b32 m0, s83
	s_add_i32 s54, s55, 0x12000
	s_ashr_i32 s0, s12, 8
	v_lshl_add_u32 v134, v10, 12, v11
	global_load_lds_dwordx4 v194, s[52:53]
	s_mov_b32 m0, s54
	s_add_i32 s34, s55, 0x2000
	global_load_lds_dwordx4 v134, s[52:53]
	s_mov_b32 m0, s55
	s_add_u32 s8, s52, 0x80000
	v_lshl_add_u32 v132, v9, 12, v11
	global_load_lds_dwordx4 v130, s[6:7]
	s_mov_b32 m0, s34
	s_addc_u32 s9, s53, 0
	s_add_i32 s4, s55, 0x14000
	global_load_lds_dwordx4 v132, s[6:7]
	s_mov_b32 m0, s4
	s_add_i32 s5, s55, 0x16000
	global_load_lds_dwordx4 v194, s[8:9]
	s_mov_b32 m0, s5
	v_writelane_b32 v250, s25, 25
	global_load_lds_dwordx4 v134, s[8:9]
	s_add_u32 s8, s6, 0x80000
	s_addc_u32 s9, s7, 0
	s_add_i32 s56, s55, 0x4000
	s_mov_b32 m0, s56
	s_add_i32 s57, s55, 0x6000
	global_load_lds_dwordx4 v130, s[8:9]
	s_mov_b32 m0, s57
	s_cmp_lg_u32 s0, 1
	global_load_lds_dwordx4 v132, s[8:9]
	s_mov_b32 s3, 0x340000
	s_mov_b32 s20, 0x480000
	s_mov_b32 s21, 0x510000
	s_mov_b32 s22, 0x5a0000
	s_mov_b32 s23, 0x630000
	s_mov_b32 s24, 0x68000
	s_mov_b32 s25, 0xd0000
	s_mov_b32 s27, 0x138000
	v_writelane_b32 v250, s12, 26
	s_cbranch_scc1 .LBB0_127
	s_barrier
